# v39 + SW attention K tiles loaded row-contiguous and re-laid out through LDS (8 cache lines per load instead of 32)
# speedup vs baseline: 1.0054x; 1.0054x over previous
; #define LAS __attribute__((address_space(3)))
; template <int MODE> ...
;     const int r32 = lane & 31, hi = lane >> 5;
;     LAS float* tab = (LAS float*)(wl + 9216);
;     const int qrow = qt + (r32 >> 4), qc = qcol0 + (r32 & 15);
;     const int qtok = MODE == 0 ? qt + r32 : qrow * 64 + qc;
;     bf16x8 qf[4];
; #pragma unroll
;     for (int ks = 0; ks < 4; ++ks) qf[ks] = *(const bf16x8*)(Qb + (size_t)qtok * qpitch + 16 * ks + 8 * hi);
;     int nt, tb0, tstep, rsA = 0, kc0 = 0, my_rs = 0, my_cs = 0;
;     if (MODE == 0) { const int t0 = qt - 128 < 0 ? 0 : qt - 128; const int t1 = qt + 160 > SEQ_ ? SEQ_ : qt + 160; tb0 = t0; nt = (t1 - t0) >> 5; tstep = 32; }
;     else { rsA = qt - 4; rsA = rsA < 0 ? 0 : (rsA > 248 ? 248 : rsA); int rsB = qt - 3; rsB = rsB < 0 ? 0 : (rsB > 248 ? 248 : rsB); nt = 8 + (rsB - rsA);
;         kc0 = qcol0 - 8; kc0 = kc0 < 0 ? 0 : (kc0 > 32 ? 32 : kc0); tb0 = rsA * 64 + kc0; tstep = 64;
;         my_rs = qrow - 4; my_rs = my_rs < 0 ? 0 : (my_rs > 248 ? 248 : my_rs); my_cs = qc - 8; my_cs = my_cs < 0 ? 0 : (my_cs > 48 ? 48 : my_cs); }
;     bf16x8 kf[4]; v4u vr[4];
.LBB0_461:
	v_mov_b32_e32 v115, v226
	s_waitcnt vmcnt(0) lgkmcnt(0)
	s_barrier
	s_and_b64 vcc, exec, s[38:39]
	v_readfirstlane_b32 s10, v115
	v_and_b32_e32 v133, 63, v115
	s_ashr_i32 s9, s10, 6
	s_mul_i32 s0, s9, 0x2c00
	v_lshrrev_b32_e32 v0, 5, v133
	v_lshlrev_b32_e32 v1, 3, v133
	v_lshrrev_b32_e32 v150, 3, v133
	v_lshlrev_b32_e32 v2, 1, v133
	v_lshlrev_b32_e32 v3, 4, v133
	s_add_i32 s8, s0, 0
	v_and_b32_e32 v113, 31, v115
	v_lshrrev_b32_e32 v134, 2, v115
	v_cmp_gt_u32_e64 s[38:39], 32, v133
	v_lshlrev_b32_e32 v112, 3, v0
	v_and_b32_e32 v114, 56, v1
	v_or_b32_e32 v151, 8, v150
	v_or_b32_e32 v152, 16, v150
	v_or_b32_e32 v153, 24, v150
	v_lshlrev_b32_e32 v116, 2, v0
	v_and_b32_e32 v135, 32, v2
	v_and_b32_e32 v117, 24, v1
	v_and_b32_e32 v136, 0x70, v3
	v_mul_u32_u24_e32 v132, 0x90, v150
	v_or_b32_e32 v154, 0xffffffc0, v133
	v_lshlrev_b32_e32 v118, 2, v133
	s_cbranch_vccnz .LBB0_592
	v_and_b32_e32 v1, 64, v230
	v_add_u32_e32 v1, 64, v1
	v_xor_b32_e32 v2, 1, v230
	v_cmp_lt_i32_e32 vcc, v2, v1
	s_lshl_b32 s11, s9, 5
	s_add_u32 s14, s6, 0x20000
	v_cndmask_b32_e32 v2, v230, v2, vcc
	v_lshlrev_b32_e32 v137, 2, v2
	v_xor_b32_e32 v2, 2, v230
	v_cmp_lt_i32_e32 vcc, v2, v1
	s_addc_u32 s15, s7, 0
	s_lshl_b32 s0, s60, 3
	v_cndmask_b32_e32 v2, v230, v2, vcc
	v_lshlrev_b32_e32 v138, 2, v2
	v_xor_b32_e32 v2, 4, v230
	v_cmp_lt_i32_e32 vcc, v2, v1
	s_or_b32 s20, s0, 4
	s_add_i32 s0, s8, 0x2400
	v_cndmask_b32_e32 v2, v230, v2, vcc
	v_lshlrev_b32_e32 v139, 2, v2
	v_xor_b32_e32 v2, 8, v230
	v_cmp_lt_i32_e32 vcc, v2, v1
	v_lshl_add_u32 v164, v133, 2, s0
	v_readlane_b32 s0, v255, 0
	v_cndmask_b32_e32 v2, v230, v2, vcc
	v_lshlrev_b32_e32 v140, 2, v2
	v_xor_b32_e32 v2, 16, v230
	v_cmp_lt_i32_e32 vcc, v2, v1
	v_mov_b32_e32 v119, v129
	v_readlane_b32 s1, v255, 1
	v_cndmask_b32_e32 v2, v230, v2, vcc
	v_lshlrev_b32_e32 v141, 2, v2
	v_xor_b32_e32 v2, 32, v230
	v_cmp_lt_i32_e32 vcc, v2, v1
	v_lshl_add_u64 v[120:121], s[0:1], 0, v[118:119]
	s_mul_i32 s0, s9, 0x2b80
	v_cndmask_b32_e32 v1, v230, v2, vcc
	v_lshlrev_b32_e32 v142, 2, v1
	v_and_or_b32 v1, v134, 3, v116
	v_mul_u32_u24_e32 v1, 0x90, v1
	v_lshl_or_b32 v0, v0, 4, s0
	v_lshlrev_b32_e32 v3, 2, v113
	v_add_u32_e32 v2, s8, v136
	v_add3_u32 v1, s8, v1, v135
	v_sub_u32_e32 v0, v0, v3
	v_readlane_b32 s0, v255, 8
	v_or_b32_e32 v143, 0x80, v116
	v_or_b32_e32 v144, 0x81, v116
	v_or_b32_e32 v145, 0x82, v116
	v_or_b32_e32 v146, 0x83, v116
	v_or_b32_e32 v147, 0x88, v116
	v_or_b32_e32 v148, 0x89, v116
	v_or_b32_e32 v149, 0x8a, v116
	v_or_b32_e32 v155, 0x8b, v116
	v_or_b32_e32 v156, 0x90, v116
	v_or_b32_e32 v157, 0x91, v116
	v_or_b32_e32 v158, 0x92, v116
	v_or_b32_e32 v159, 0x93, v116
	v_or_b32_e32 v160, 0x98, v116
	v_or_b32_e32 v161, 0x99, v116
	v_or_b32_e32 v162, 0x9a, v116
	v_or_b32_e32 v163, 0x9b, v116
	v_or_b32_e32 v165, 0xffffffc0, v133
	v_add_u32_e32 v119, s0, v0
	s_sub_i32 s21, 0, s11
	v_lshlrev_b32_e32 v122, 1, v114
	v_add_u32_e32 v166, v2, v132
	v_add_u32_e32 v167, v1, v117
	s_mul_i32 s98, s9, 0x1200
	s_add_i32 s98, s98, 0x16000
	v_add3_u32 v224, v136, v132, s98
	v_mul_u32_u24_e32 v225, 0x90, v113
	v_lshl_add_u32 v225, v116, 2, v225
	v_add_u32_e32 v225, s98, v225
	s_mov_b32 s29, s90
	s_branch .LBB0_464

; #define SA_LOAD(tbase) do { const bf16* kp_ = Kp + (size_t)((tbase) + r32) * kvpitch + 8 * hi; \
;         _Pragma("unroll") for (int ks = 0; ks < 4; ++ks) kf[ks] = *(const bf16x8*)(kp_ + 16 * ks); \
;         _Pragma("unroll") for (int e = 0; e < 4; ++e) { const int c = lane + 64 * e; vr[e] = *(const v4u*)(Vp + (size_t)((tbase) + (c >> 3)) * kvpitch + (c & 7) * 8); } } while (0)
; template <int MODE> ...
;     ...
;     const int qrow = qt + (r32 >> 4), qc = qcol0 + (r32 & 15);
;     const int qtok = MODE == 0 ? qt + r32 : qrow * 64 + qc;
;     bf16x8 qf[4];
; #pragma unroll
;     for (int ks = 0; ks < 4; ++ks) qf[ks] = *(const bf16x8*)(Qb + (size_t)qtok * qpitch + 16 * ks + 8 * hi);
;     int nt, tb0, tstep, rsA = 0, kc0 = 0, my_rs = 0, my_cs = 0;
;     if (MODE == 0) { const int t0 = qt - 128 < 0 ? 0 : qt - 128; const int t1 = qt + 160 > SEQ_ ? SEQ_ : qt + 160; tb0 = t0; nt = (t1 - t0) >> 5; tstep = 32; }
;     else { rsA = qt - 4; rsA = rsA < 0 ? 0 : (rsA > 248 ? 248 : rsA); int rsB = qt - 3; rsB = rsB < 0 ? 0 : (rsB > 248 ? 248 : rsB); nt = 8 + (rsB - rsA);
;         kc0 = qcol0 - 8; kc0 = kc0 < 0 ? 0 : (kc0 > 32 ? 32 : kc0); tb0 = rsA * 64 + kc0; tstep = 64;
;         my_rs = qrow - 4; my_rs = my_rs < 0 ? 0 : (my_rs > 248 ? 248 : my_rs); my_cs = qc - 8; my_cs = my_cs < 0 ? 0 : (my_cs > 48 ? 48 : my_cs); }
;     bf16x8 kf[4]; v4u vr[4];
;     ...
;     SA_LOAD(tb0);
;     float bmx = -1e30f;
;     for (int e = lane; e < ntab; e += 64) { const float tv_ = gtab[e] * tabscale; tab[e] = tv_; bmx = fmaxf(bmx, tv_); }
; #pragma unroll
;     for (int o_ = 1; o_ < 64; o_ <<= 1) bmx = fmaxf(bmx, __shfl_xor(bmx, o_));
; __global__ void __launch_bounds__(512) mega_fwd(Args args) {
;     ...
;                 const int u = uu % 768; const int qb = u & 63, h = (u >> 6) % 6, b = u / 384; const int qt = qb * 256 + wave * 32; const size_t rb = (size_t)b * SEQ_;
;                 small_attn_wave<0>(QKV + pg8::OFF_QB + rb * 384 + h * 64, 384, QKV + pg8::OFF_KB + rb * 128 + (h / 3) * 64, QKV + pg8::OFF_VB + rb * 128 + (h / 3) * 64, 128,
;                                    YB + rb * 1024 + 256 + h * 64, qt, 0, (const float*)(ws + WS_SWB) + h * 260, 257, 1.0f, args.in[I_SINK][l * 6 + h] * LOG2E_, GSS + (size_t)(l * 3 + 1) * MT + rb, (const unsigned*)(ws + WS_KMAX) + ((l * 2 + 1) * 4 + h / 3) * 2, wl, lane);
.LBB0_464:
	s_mul_hi_i32 s0, s29, 0x2aaaaaab
	s_lshr_b32 s1, s0, 31
	s_lshr_b32 s0, s0, 7
	s_add_i32 s0, s0, s1
	s_mulk_i32 s0, 0x300
	s_sub_i32 s4, s29, s0
	s_lshr_b32 s0, s4, 6
	s_bfe_i32 s1, s0, 0x80000
	s_mul_i32 s1, s1, 43
	s_bfe_u32 s5, s1, 0x1000f
	s_bfe_u32 s1, s1, 0x80008
	s_add_i32 s1, s1, s5
	s_mul_i32 s1, s1, 6
	s_sub_i32 s30, s0, s1
	s_mul_i32 s0, s4, 0x2aab
	s_lshr_b32 s1, s0, 31
	s_ashr_i32 s0, s0, 22
	s_add_i32 s40, s0, s1
	s_lshl_b32 s0, s4, 8
	s_and_b32 s5, s0, 0x3f00
	s_add_i32 s31, s5, s11
	s_ashr_i32 s41, s40, 31
	s_mul_i32 s1, s40, 0xc00000
	v_readlane_b32 s12, v254, 3
	s_sext_i32_i8 s37, s30
	s_mul_hi_i32 s0, s40, 0xc00000
	s_add_u32 s34, s12, s1
	v_readlane_b32 s1, v254, 4
	s_addc_u32 s44, s1, s0
	s_lshl_b32 s0, s37, 6
	s_ashr_i32 s1, s0, 31
	s_lshl_b64 s[42:43], s[0:1], 1
	s_add_u32 s0, s34, s42
	s_addc_u32 s1, s44, s43
	s_lshl_b64 s[46:47], s[40:41], 22
	v_readlane_b32 s12, v254, 5
	s_add_u32 s50, s12, s46
	v_readlane_b32 s12, v254, 6
	s_addc_u32 s51, s12, s47
	s_bfe_i32 s30, s30, 0x80000
	s_mulk_i32 s30, 0x56
	s_bfe_u32 s34, s30, 0x1000f
	s_bfe_u32 s30, s30, 0x80008
	s_add_i32 s30, s30, s34
	s_sext_i32_i8 s34, s30
	s_lshl_b32 s44, s34, 6
	s_ashr_i32 s45, s44, 31
	s_lshl_b64 s[48:49], s[44:45], 1
	s_add_u32 s44, s50, s48
	s_addc_u32 s45, s51, s49
	v_readlane_b32 s12, v254, 7
	s_add_u32 s30, s12, s46
	v_readlane_b32 s12, v254, 8
	s_addc_u32 s47, s12, s47
	s_add_u32 s46, s30, s48
	s_mul_i32 s30, s60, 6
	s_addc_u32 s47, s47, s49
	s_add_i32 s50, s30, s37
	s_mul_i32 s48, s37, 0x104
	s_ashr_i32 s51, s50, 31
	s_ashr_i32 s49, s48, 31
	s_lshl_b64 s[50:51], s[50:51], 2
	s_add_u32 s50, s58, s50
	v_or_b32_e32 v124, s31, v113
	v_mov_b64_e32 v[0:1], s[0:1]
	s_movk_i32 s0, 0x300
	s_addc_u32 s51, s59, s51
	v_mad_i64_i32 v[0:1], s[0:1], v124, s0, v[0:1]
	v_lshlrev_b32_e32 v128, 1, v112
	s_max_i32 s30, s31, 0x80
	v_lshl_add_u64 v[0:1], v[0:1], 0, v[128:129]
	s_add_i32 s37, s30, 0xffffff80
	global_load_dword v168, v129, s[50:51]
	global_load_dwordx4 v[64:67], v[0:1], off
	global_load_dwordx4 v[68:71], v[0:1], off offset:32
	global_load_dwordx4 v[72:75], v[0:1], off offset:64
	global_load_dwordx4 v[76:79], v[0:1], off offset:96
	v_or_b32_e32 v0, s37, v113
	v_mov_b32_e32 v1, v129
	v_lshlrev_b64 v[0:1], 8, v[0:1]
	v_lshl_add_u64 v[0:1], s[44:45], 0, v[0:1]
	v_lshl_add_u64 v[0:1], v[0:1], 0, v[128:129]
	global_load_dwordx4 v[80:83], v[0:1], off
	global_load_dwordx4 v[84:87], v[0:1], off offset:32
	global_load_dwordx4 v[88:91], v[0:1], off offset:64
	global_load_dwordx4 v[92:95], v[0:1], off offset:96
	v_mov_b32_e32 v123, v129
	v_or_b32_e32 v0, s37, v150
	v_mov_b32_e32 v1, v129
	v_lshl_add_u64 v[126:127], s[46:47], 0, v[122:123]
	v_lshl_add_u64 v[176:177], s[44:45], 0, v[122:123]
	v_lshlrev_b64 v[0:1], 8, v[0:1]
	v_or_b32_e32 v2, s37, v151
	v_mov_b32_e32 v3, v129
	v_lshl_add_u64 v[0:1], v[126:127], 0, v[0:1]
	v_lshlrev_b64 v[2:3], 8, v[2:3]
	v_lshl_add_u64 v[2:3], v[126:127], 0, v[2:3]
	global_load_dwordx4 v[96:99], v[0:1], off
	global_load_dwordx4 v[100:103], v[2:3], off
	v_or_b32_e32 v0, s37, v152
	v_mov_b32_e32 v1, v129
	v_lshlrev_b64 v[0:1], 8, v[0:1]
	v_or_b32_e32 v2, s37, v153
	v_mov_b32_e32 v3, v129
	v_lshl_add_u64 v[0:1], v[126:127], 0, v[0:1]
	v_lshlrev_b64 v[2:3], 8, v[2:3]
	v_lshl_add_u64 v[2:3], v[126:127], 0, v[2:3]
	global_load_dwordx4 v[104:107], v[0:1], off
	global_load_dwordx4 v[108:111], v[2:3], off
	v_ashrrev_i32_e32 v125, 31, v124
	v_lshl_add_u64 v[0:1], s[48:49], 2, v[120:121]
	v_mov_b32_e32 v2, 0xf149f2ca
	s_movk_i32 s46, 0xc0
	global_load_dword v5, v[0:1], off
	global_load_dword v6, v[0:1], off offset:256
	global_load_dword v7, v[0:1], off offset:512
	global_load_dword v8, v[0:1], off offset:768
	s_mov_b64 s[0:1], exec
	v_cmp_eq_u32_e32 vcc, 0, v133
	s_and_b64 exec, exec, vcc
	global_load_dword v9, v[0:1], off offset:1024
	s_mov_b64 exec, s[0:1]
	s_waitcnt vmcnt(0)
	ds_write_b32 v164, v5
	ds_write_b32 v164, v6 offset:256
	ds_write_b32 v164, v7 offset:512
	ds_write_b32 v164, v8 offset:768
	v_max_f32_e32 v5, v5, v5
	v_max_f32_e32 v6, v6, v6
	v_max_f32_e32 v7, v7, v7
	v_max_f32_e32 v8, v8, v8
	v_max_f32_e32 v2, v2, v5
	v_max_f32_e32 v2, v2, v6
	v_max_f32_e32 v2, v2, v7
	v_max_f32_e32 v2, v2, v8
	s_and_b64 exec, exec, vcc
	ds_write_b32 v164, v9 offset:1024
	v_max_f32_e32 v9, v9, v9
	v_max_f32_e32 v2, v2, v9
	s_mov_b64 exec, s[0:1]
	s_add_i32 s0, s20, s34
	s_lshl_b32 s34, s0, 1
	s_lshl_b64 s[0:1], s[34:35], 2
	ds_bpermute_b32 v0, v137, v2
	s_add_u32 s0, s76, s0
	s_addc_u32 s1, s77, s1
	global_load_dwordx2 v[16:17], v129, s[0:1]
	v_max_f32_e32 v1, v2, v2
	s_waitcnt lgkmcnt(0)
	v_max_f32_e32 v0, v0, v0
	v_max_f32_e32 v0, v1, v0
	ds_bpermute_b32 v1, v138, v0
	v_and_b32_e32 v2, 0xffff0000, v65
	v_mul_f32_e32 v2, v2, v2
	s_sub_i32 s0, s30, s31
	s_sub_i32 s34, s0, 32
	s_waitcnt lgkmcnt(0)
	v_max_f32_e32 v1, v1, v1
	v_max_f32_e32 v0, v0, v1
	ds_bpermute_b32 v1, v139, v0
	s_mov_b64 s[0:1], -1
	s_cmpk_gt_u32 s34, 0xc0
	ds_write_b128 v166, v[96:99]
	ds_write_b128 v166, v[100:103] offset:1152
	ds_write_b128 v166, v[104:107] offset:2304
	ds_write_b128 v166, v[108:111] offset:3456
	s_waitcnt lgkmcnt(4)
	v_max_f32_e32 v1, v1, v1
	v_max_f32_e32 v0, v0, v1
	ds_bpermute_b32 v1, v140, v0
	s_waitcnt lgkmcnt(0)
	v_max_f32_e32 v1, v1, v1
	v_max_f32_e32 v0, v0, v1
	ds_bpermute_b32 v1, v141, v0
	s_waitcnt lgkmcnt(0)
; #define SA_LOAD(tbase) do { const bf16* kp_ = Kp + (size_t)((tbase) + r32) * kvpitch + 8 * hi; \
;         _Pragma("unroll") for (int ks = 0; ks < 4; ++ks) kf[ks] = *(const bf16x8*)(kp_ + 16 * ks); \
;         _Pragma("unroll") for (int e = 0; e < 4; ++e) { const int c = lane + 64 * e; vr[e] = *(const v4u*)(Vp + (size_t)((tbase) + (c >> 3)) * kvpitch + (c & 7) * 8); } } while (0)
; template <int MODE> ...
;     ...
;     SA_LOAD(tb0);
;     float bmx = -1e30f;
;     for (int e = lane; e < ntab; e += 64) { const float tv_ = gtab[e] * tabscale; tab[e] = tv_; bmx = fmaxf(bmx, tv_); }
; #pragma unroll
;     for (int o_ = 1; o_ < 64; o_ <<= 1) bmx = fmaxf(bmx, __shfl_xor(bmx, o_));
;     float ref;
;     { float qs = 0.f;
; #pragma unroll
;       for (int ks = 0; ks < 4; ++ks) { const v4u qw = __builtin_bit_cast(v4u, qf[ks]);
; #pragma unroll
;           for (int e = 0; e < 4; ++e) { const float lo_ = __uint_as_float(qw[e] << 16), hi_ = __uint_as_float(qw[e] & 0xffff0000u); qs += lo_ * lo_ + hi_ * hi_; } }
;       auto rr = __builtin_amdgcn_permlane32_swap(__float_as_uint(qs), __float_as_uint(qs), false, false); qs = __uint_as_float(rr[0]) + __uint_as_float(rr[1]);
;       const float k2 = __uint_as_float(kmax2[0]) + __uint_as_float(kmax2[1]);
;       ref = fminf(__builtin_sqrtf(qs * k2) * 1.03f + bmx, 110.0f); }
	v_max_f32_e32 v1, v1, v1
	v_max_f32_e32 v18, v0, v1
	v_and_b32_e32 v1, 0xffff0000, v64
	v_lshlrev_b32_e32 v0, 16, v64
	v_mul_f32_e32 v1, v1, v1
	v_fmac_f32_e32 v1, v0, v0
	v_lshlrev_b32_e32 v0, 16, v65
	v_fmac_f32_e32 v2, v0, v0
	v_add_f32_e32 v0, v1, v2
	v_and_b32_e32 v2, 0xffff0000, v66
	v_lshlrev_b32_e32 v1, 16, v66
	v_mul_f32_e32 v2, v2, v2
	v_fmac_f32_e32 v2, v1, v1
	v_add_f32_e32 v0, v2, v0
	v_and_b32_e32 v2, 0xffff0000, v67
	v_lshlrev_b32_e32 v1, 16, v67
	v_mul_f32_e32 v2, v2, v2
	v_fmac_f32_e32 v2, v1, v1
	v_add_f32_e32 v0, v2, v0
	v_and_b32_e32 v2, 0xffff0000, v68
	v_lshlrev_b32_e32 v1, 16, v68
	v_mul_f32_e32 v2, v2, v2
	v_fmac_f32_e32 v2, v1, v1
	v_add_f32_e32 v0, v2, v0
	v_and_b32_e32 v2, 0xffff0000, v69
	v_lshlrev_b32_e32 v1, 16, v69
	v_mul_f32_e32 v2, v2, v2
	v_fmac_f32_e32 v2, v1, v1
	v_add_f32_e32 v0, v2, v0
	v_and_b32_e32 v2, 0xffff0000, v70
	v_lshlrev_b32_e32 v1, 16, v70
	v_mul_f32_e32 v2, v2, v2
	v_fmac_f32_e32 v2, v1, v1
	v_add_f32_e32 v0, v2, v0
	v_and_b32_e32 v2, 0xffff0000, v71
	v_lshlrev_b32_e32 v1, 16, v71
	v_mul_f32_e32 v2, v2, v2
	v_fmac_f32_e32 v2, v1, v1
	v_add_f32_e32 v0, v2, v0
	v_and_b32_e32 v2, 0xffff0000, v72
	v_lshlrev_b32_e32 v1, 16, v72
	v_mul_f32_e32 v2, v2, v2
	v_fmac_f32_e32 v2, v1, v1
	v_add_f32_e32 v0, v2, v0
	v_and_b32_e32 v2, 0xffff0000, v73
	v_lshlrev_b32_e32 v1, 16, v73
	v_mul_f32_e32 v2, v2, v2
	v_fmac_f32_e32 v2, v1, v1
	v_add_f32_e32 v0, v2, v0
	v_and_b32_e32 v2, 0xffff0000, v74
	v_lshlrev_b32_e32 v1, 16, v74
	v_mul_f32_e32 v2, v2, v2
	v_fmac_f32_e32 v2, v1, v1
	v_add_f32_e32 v0, v2, v0
	v_and_b32_e32 v2, 0xffff0000, v75
	v_lshlrev_b32_e32 v1, 16, v75
	v_mul_f32_e32 v2, v2, v2
	v_fmac_f32_e32 v2, v1, v1
	v_add_f32_e32 v0, v2, v0
	v_and_b32_e32 v2, 0xffff0000, v76
	v_lshlrev_b32_e32 v1, 16, v76
	v_mul_f32_e32 v2, v2, v2
	v_fmac_f32_e32 v2, v1, v1
	v_add_f32_e32 v0, v2, v0
	v_and_b32_e32 v2, 0xffff0000, v77
	v_lshlrev_b32_e32 v1, 16, v77
	v_mul_f32_e32 v2, v2, v2
	v_fmac_f32_e32 v2, v1, v1
	v_add_f32_e32 v0, v2, v0
	v_and_b32_e32 v2, 0xffff0000, v78
	v_lshlrev_b32_e32 v1, 16, v78
	v_mul_f32_e32 v2, v2, v2
	v_fmac_f32_e32 v2, v1, v1
	v_add_f32_e32 v0, v2, v0
	v_and_b32_e32 v2, 0xffff0000, v79
	ds_bpermute_b32 v19, v142, v18
	v_lshlrev_b32_e32 v1, 16, v79
	v_mul_f32_e32 v2, v2, v2
	v_fmac_f32_e32 v2, v1, v1
	v_add_f32_e32 v20, v2, v0
	v_mov_b32_e32 v21, v20
	s_nop 1
	v_permlane32_swap_b32_e32 v20, v21
	s_cbranch_scc0 .LBB0_500
	v_sub_u32_e32 v0, s37, v124
	v_add_u32_e32 v22, v0, v116
	v_add_u32_e32 v0, 0x80, v22
	v_cmp_gt_u32_e32 vcc, s33, v0
	v_mov_b32_e32 v1, 0xf149f2ca
	v_mov_b32_e32 v0, 0xf149f2ca
	s_and_saveexec_b64 s[0:1], vcc
	v_sub_u32_e32 v0, s30, v124
	v_add_u32_e32 v0, v0, v143
	v_lshl_add_u32 v0, v0, 2, s8
	ds_read_b32 v0, v0 offset:8704
	s_or_b64 exec, exec, s[0:1]
	v_add_u32_e32 v2, 0x81, v22
	v_cmp_gt_u32_e32 vcc, s33, v2
	s_and_saveexec_b64 s[0:1], vcc
	v_sub_u32_e32 v1, s30, v124
	v_add_u32_e32 v1, v1, v144
	v_lshl_add_u32 v1, v1, 2, s8
	ds_read_b32 v1, v1 offset:8704
	s_or_b64 exec, exec, s[0:1]
	v_add_u32_e32 v2, 0x82, v22
	v_cmp_gt_u32_e32 vcc, s33, v2
	v_mov_b32_e32 v3, 0xf149f2ca
	v_mov_b32_e32 v2, 0xf149f2ca
	s_and_saveexec_b64 s[0:1], vcc
	v_sub_u32_e32 v2, s30, v124
	v_add_u32_e32 v2, v2, v145
	v_lshl_add_u32 v2, v2, 2, s8
	ds_read_b32 v2, v2 offset:8704
	s_or_b64 exec, exec, s[0:1]
	v_add_u32_e32 v4, 0x83, v22
	v_cmp_gt_u32_e32 vcc, s33, v4
	s_and_saveexec_b64 s[0:1], vcc
	v_sub_u32_e32 v3, s30, v124
	v_add_u32_e32 v3, v3, v146
	v_lshl_add_u32 v3, v3, 2, s8
	ds_read_b32 v3, v3 offset:8704
	s_or_b64 exec, exec, s[0:1]
	v_add_u32_e32 v4, 0x88, v22
	v_cmp_gt_u32_e32 vcc, s33, v4
	v_mov_b32_e32 v5, 0xf149f2ca
	v_mov_b32_e32 v4, 0xf149f2ca
	s_and_saveexec_b64 s[0:1], vcc
	v_sub_u32_e32 v4, s30, v124
	v_add_u32_e32 v4, v4, v147
	v_lshl_add_u32 v4, v4, 2, s8
	ds_read_b32 v4, v4 offset:8704
	s_or_b64 exec, exec, s[0:1]
	v_add_u32_e32 v6, 0x89, v22
	v_cmp_gt_u32_e32 vcc, s33, v6
	s_and_saveexec_b64 s[0:1], vcc
	v_sub_u32_e32 v5, s30, v124
	v_add_u32_e32 v5, v5, v148
	v_lshl_add_u32 v5, v5, 2, s8
	ds_read_b32 v5, v5 offset:8704
	s_or_b64 exec, exec, s[0:1]
	v_add_u32_e32 v6, 0x8a, v22
	v_cmp_gt_u32_e32 vcc, s33, v6
	v_mov_b32_e32 v7, 0xf149f2ca
	v_mov_b32_e32 v6, 0xf149f2ca
	s_and_saveexec_b64 s[0:1], vcc
	v_sub_u32_e32 v6, s30, v124
	v_add_u32_e32 v6, v6, v149
	v_lshl_add_u32 v6, v6, 2, s8
	ds_read_b32 v6, v6 offset:8704
	s_or_b64 exec, exec, s[0:1]
	v_add_u32_e32 v8, 0x8b, v22
	v_cmp_gt_u32_e32 vcc, s33, v8
	s_and_saveexec_b64 s[0:1], vcc
	v_sub_u32_e32 v7, s30, v124
	v_add_u32_e32 v7, v7, v155
	v_lshl_add_u32 v7, v7, 2, s8
	ds_read_b32 v7, v7 offset:8704
	s_or_b64 exec, exec, s[0:1]
	v_add_u32_e32 v8, 0x90, v22
	v_cmp_gt_u32_e32 vcc, s33, v8
	v_mov_b32_e32 v9, 0xf149f2ca
	v_mov_b32_e32 v8, 0xf149f2ca
	s_and_saveexec_b64 s[0:1], vcc
	v_sub_u32_e32 v8, s30, v124
	v_add_u32_e32 v8, v8, v156
	v_lshl_add_u32 v8, v8, 2, s8
	ds_read_b32 v8, v8 offset:8704
	s_or_b64 exec, exec, s[0:1]
	v_add_u32_e32 v10, 0x91, v22
	v_cmp_gt_u32_e32 vcc, s33, v10
	s_and_saveexec_b64 s[0:1], vcc
	v_sub_u32_e32 v9, s30, v124
	v_add_u32_e32 v9, v9, v157
	v_lshl_add_u32 v9, v9, 2, s8
	ds_read_b32 v9, v9 offset:8704
	s_or_b64 exec, exec, s[0:1]
	v_add_u32_e32 v10, 0x92, v22
	v_cmp_gt_u32_e32 vcc, s33, v10
	v_mov_b32_e32 v11, 0xf149f2ca
	v_mov_b32_e32 v10, 0xf149f2ca
	s_and_saveexec_b64 s[0:1], vcc
	v_sub_u32_e32 v10, s30, v124
	v_add_u32_e32 v10, v10, v158
	v_lshl_add_u32 v10, v10, 2, s8
	ds_read_b32 v10, v10 offset:8704
	s_or_b64 exec, exec, s[0:1]
	v_add_u32_e32 v12, 0x93, v22
	v_cmp_gt_u32_e32 vcc, s33, v12
	s_and_saveexec_b64 s[0:1], vcc
	v_sub_u32_e32 v11, s30, v124
	v_add_u32_e32 v11, v11, v159
	v_lshl_add_u32 v11, v11, 2, s8
	ds_read_b32 v11, v11 offset:8704
	s_or_b64 exec, exec, s[0:1]
	v_add_u32_e32 v12, 0x98, v22
	v_cmp_gt_u32_e32 vcc, s33, v12
	v_mov_b32_e32 v13, 0xf149f2ca
	v_mov_b32_e32 v12, 0xf149f2ca
	s_and_saveexec_b64 s[0:1], vcc
	v_sub_u32_e32 v12, s30, v124
	v_add_u32_e32 v12, v12, v160
	v_lshl_add_u32 v12, v12, 2, s8
	ds_read_b32 v12, v12 offset:8704
	s_or_b64 exec, exec, s[0:1]
	v_add_u32_e32 v14, 0x99, v22
	v_cmp_gt_u32_e32 vcc, s33, v14
	s_and_saveexec_b64 s[0:1], vcc
	v_sub_u32_e32 v13, s30, v124
	v_add_u32_e32 v13, v13, v161
	v_lshl_add_u32 v13, v13, 2, s8
	ds_read_b32 v13, v13 offset:8704
	s_or_b64 exec, exec, s[0:1]
	v_add_u32_e32 v14, 0x9a, v22
	v_cmp_gt_u32_e32 vcc, s33, v14
	v_mov_b32_e32 v15, 0xf149f2ca
	v_mov_b32_e32 v14, 0xf149f2ca
	s_and_saveexec_b64 s[0:1], vcc
	v_sub_u32_e32 v14, s30, v124
	v_add_u32_e32 v14, v14, v162
	v_lshl_add_u32 v14, v14, 2, s8
	ds_read_b32 v14, v14 offset:8704
	s_or_b64 exec, exec, s[0:1]
	v_add_u32_e32 v22, 0x9b, v22
	v_cmp_gt_u32_e32 vcc, s33, v22
	s_and_saveexec_b64 s[0:1], vcc
	v_sub_u32_e32 v15, s30, v124
	v_add_u32_e32 v15, v15, v163
	v_lshl_add_u32 v15, v15, 2, s8
	ds_read_b32 v15, v15 offset:8704
	s_or_b64 exec, exec, s[0:1]
	s_mov_b64 s[0:1], 0

; #define SA_LOAD(tbase) do { const bf16* kp_ = Kp + (size_t)((tbase) + r32) * kvpitch + 8 * hi; \
;         _Pragma("unroll") for (int ks = 0; ks < 4; ++ks) kf[ks] = *(const bf16x8*)(kp_ + 16 * ks); \
;         _Pragma("unroll") for (int e = 0; e < 4; ++e) { const int c = lane + 64 * e; vr[e] = *(const v4u*)(Vp + (size_t)((tbase) + (c >> 3)) * kvpitch + (c & 7) * 8); } } while (0)
; template <int MODE> ...
;     ...
;     if (nt > 1) SA_LOAD(tb0 + tstep);
.LBB0_502:
	s_waitcnt lgkmcnt(0)
	v_mfma_f32_32x32x16_bf16 v[0:15], v[80:83], v[64:67], v[0:15]
	s_min_i32 s0, s31, 0x3f60
	s_sub_i32 s0, s0, s30
	s_addk_i32 s0, 0x120
	s_ashr_i32 s31, s0, 5
	s_cmp_lt_i32 s31, 2
	v_mfma_f32_32x32x16_bf16 v[0:15], v[84:87], v[68:71], v[0:15]
	v_mfma_f32_32x32x16_bf16 v[0:15], v[88:91], v[72:75], v[0:15]
	v_mfma_f32_32x32x16_bf16 v[0:15], v[92:95], v[76:79], v[0:15]
	s_cbranch_scc1 .LBB0_504
	s_add_i32 s0, s30, 0xffffffa0
	v_or_b32_e32 v22, s0, v150
	v_mov_b32_e32 v23, v129
	v_lshlrev_b64 v[22:23], 8, v[22:23]
	v_lshl_add_u64 v[22:23], v[176:177], 0, v[22:23]
	global_load_dwordx4 v[208:211], v[22:23], off
	v_or_b32_e32 v24, s0, v151
	v_mov_b32_e32 v25, v129
	v_lshlrev_b64 v[24:25], 8, v[24:25]
	v_lshl_add_u64 v[24:25], v[176:177], 0, v[24:25]
	global_load_dwordx4 v[212:215], v[24:25], off
	v_or_b32_e32 v22, s0, v152
	v_mov_b32_e32 v23, v129
	v_lshlrev_b64 v[22:23], 8, v[22:23]
	v_lshl_add_u64 v[22:23], v[176:177], 0, v[22:23]
	global_load_dwordx4 v[216:219], v[22:23], off
	v_or_b32_e32 v24, s0, v153
	v_mov_b32_e32 v25, v129
	v_lshlrev_b64 v[24:25], 8, v[24:25]
	v_lshl_add_u64 v[24:25], v[176:177], 0, v[24:25]
	global_load_dwordx4 v[220:223], v[24:25], off
	v_or_b32_e32 v22, s0, v150
	v_mov_b32_e32 v23, v129
	v_lshlrev_b64 v[22:23], 8, v[22:23]
	v_or_b32_e32 v24, s0, v151
	v_mov_b32_e32 v25, v129
	v_lshl_add_u64 v[22:23], v[126:127], 0, v[22:23]
	v_lshlrev_b64 v[24:25], 8, v[24:25]
	v_lshl_add_u64 v[24:25], v[126:127], 0, v[24:25]
	global_load_dwordx4 v[96:99], v[22:23], off
	global_load_dwordx4 v[100:103], v[24:25], off
	v_or_b32_e32 v22, s0, v152
	v_mov_b32_e32 v23, v129
	v_lshlrev_b64 v[22:23], 8, v[22:23]
	v_or_b32_e32 v24, s0, v153
	v_mov_b32_e32 v25, v129
	v_lshl_add_u64 v[22:23], v[126:127], 0, v[22:23]
	v_lshlrev_b64 v[24:25], 8, v[24:25]
	v_lshl_add_u64 v[24:25], v[126:127], 0, v[24:25]
	global_load_dwordx4 v[104:107], v[22:23], off
	global_load_dwordx4 v[108:111], v[24:25], off

.LBB0_506:
	s_add_i32 s0, s45, 1
	s_cmp_ge_i32 s0, s31
	s_cselect_b64 s[0:1], -1, 0
	s_and_b64 vcc, exec, s[0:1]
	s_cbranch_vccnz .LBB0_545
	s_add_i32 s4, s44, s30
	s_cmpk_lt_u32 s4, 0xc1
	s_mov_b64 s[4:5], -1
	s_waitcnt vmcnt(4)
	ds_write_b128 v224, v[208:211]
	ds_write_b128 v224, v[212:215] offset:1152
	ds_write_b128 v224, v[216:219] offset:2304
	ds_write_b128 v224, v[220:223] offset:3456
	ds_read_b128 v[80:83], v225
	ds_read_b128 v[84:87], v225 offset:32
	ds_read_b128 v[88:91], v225 offset:64
	ds_read_b128 v[92:95], v225 offset:96
	s_waitcnt vmcnt(3)
	ds_write_b128 v166, v[96:99] offset:4608
	s_waitcnt vmcnt(2)
	ds_write_b128 v166, v[100:103] offset:5760
	s_waitcnt vmcnt(1)
	ds_write_b128 v166, v[104:107] offset:6912
	s_waitcnt vmcnt(0)
	ds_write_b128 v166, v[108:111] offset:8064
	s_cbranch_scc1 .LBB0_541
	v_add_u32_e32 v171, s30, v170
	v_add_u32_e32 v48, 32, v171
	v_cmp_gt_u32_e32 vcc, s33, v48
	v_mov_b32_e32 v49, 0xf149f2ca
	v_mov_b32_e32 v48, 0xf149f2ca
	s_and_saveexec_b64 s[4:5], vcc
	ds_read_b32 v48, v128
	s_or_b64 exec, exec, s[4:5]
	v_add_u32_e32 v50, 33, v171
	v_cmp_gt_u32_e32 vcc, s33, v50
	s_and_saveexec_b64 s[4:5], vcc
	ds_read_b32 v49, v128 offset:4
	s_or_b64 exec, exec, s[4:5]
	v_add_u32_e32 v50, 34, v171
	v_cmp_gt_u32_e32 vcc, s33, v50
	v_mov_b32_e32 v51, 0xf149f2ca
	v_mov_b32_e32 v50, 0xf149f2ca
	s_and_saveexec_b64 s[4:5], vcc
	ds_read_b32 v50, v128 offset:8
	s_or_b64 exec, exec, s[4:5]
	v_add_u32_e32 v52, 35, v171
	v_cmp_gt_u32_e32 vcc, s33, v52
	s_and_saveexec_b64 s[4:5], vcc
	ds_read_b32 v51, v128 offset:12
	s_or_b64 exec, exec, s[4:5]
	v_add_u32_e32 v52, 40, v171
	v_cmp_gt_u32_e32 vcc, s33, v52
	v_mov_b32_e32 v53, 0xf149f2ca
	v_mov_b32_e32 v52, 0xf149f2ca
	s_and_saveexec_b64 s[4:5], vcc
	ds_read_b32 v52, v128 offset:32
	s_or_b64 exec, exec, s[4:5]
	v_add_u32_e32 v54, 41, v171
	v_cmp_gt_u32_e32 vcc, s33, v54
	s_and_saveexec_b64 s[4:5], vcc
	ds_read_b32 v53, v128 offset:36
	s_or_b64 exec, exec, s[4:5]
	v_add_u32_e32 v54, 42, v171
	v_cmp_gt_u32_e32 vcc, s33, v54
	v_mov_b32_e32 v55, 0xf149f2ca
	v_mov_b32_e32 v54, 0xf149f2ca
	s_and_saveexec_b64 s[4:5], vcc
	ds_read_b32 v54, v128 offset:40
	s_or_b64 exec, exec, s[4:5]
	v_add_u32_e32 v56, 43, v171
	v_cmp_gt_u32_e32 vcc, s33, v56
	s_and_saveexec_b64 s[4:5], vcc
	ds_read_b32 v55, v128 offset:44
	s_or_b64 exec, exec, s[4:5]
	v_add_u32_e32 v56, 48, v171
	v_cmp_gt_u32_e32 vcc, s33, v56
	v_mov_b32_e32 v57, 0xf149f2ca
	v_mov_b32_e32 v56, 0xf149f2ca
	s_and_saveexec_b64 s[4:5], vcc
	ds_read_b32 v56, v128 offset:64
	s_or_b64 exec, exec, s[4:5]
	v_add_u32_e32 v58, 49, v171
	v_cmp_gt_u32_e32 vcc, s33, v58
	s_and_saveexec_b64 s[4:5], vcc
	ds_read_b32 v57, v128 offset:68
	s_or_b64 exec, exec, s[4:5]
	v_add_u32_e32 v58, 50, v171
	v_cmp_gt_u32_e32 vcc, s33, v58
	v_mov_b32_e32 v59, 0xf149f2ca
	v_mov_b32_e32 v58, 0xf149f2ca
	s_and_saveexec_b64 s[4:5], vcc
	ds_read_b32 v58, v128 offset:72
	s_or_b64 exec, exec, s[4:5]
	v_add_u32_e32 v60, 51, v171
	v_cmp_gt_u32_e32 vcc, s33, v60
	s_and_saveexec_b64 s[4:5], vcc
	ds_read_b32 v59, v128 offset:76
	s_or_b64 exec, exec, s[4:5]
	v_add_u32_e32 v60, 56, v171
	v_cmp_gt_u32_e32 vcc, s33, v60
	v_mov_b32_e32 v61, 0xf149f2ca
	v_mov_b32_e32 v60, 0xf149f2ca
	s_and_saveexec_b64 s[4:5], vcc
	ds_read_b32 v60, v128 offset:96
	s_or_b64 exec, exec, s[4:5]
	v_add_u32_e32 v62, 57, v171
	v_cmp_gt_u32_e32 vcc, s33, v62
	s_and_saveexec_b64 s[4:5], vcc
	ds_read_b32 v61, v128 offset:100
	s_or_b64 exec, exec, s[4:5]
	v_add_u32_e32 v62, 58, v171
	v_cmp_gt_u32_e32 vcc, s33, v62
	v_mov_b32_e32 v63, 0xf149f2ca
	v_mov_b32_e32 v62, 0xf149f2ca
	s_and_saveexec_b64 s[4:5], vcc
	ds_read_b32 v62, v128 offset:104
	s_or_b64 exec, exec, s[4:5]
	v_add_u32_e32 v171, 59, v171
	v_cmp_gt_u32_e32 vcc, s33, v171
	s_and_saveexec_b64 s[4:5], vcc
	ds_read_b32 v63, v128 offset:108
	s_or_b64 exec, exec, s[4:5]
	s_mov_b64 s[4:5], 0

.LBB0_543:
	s_waitcnt lgkmcnt(0)
	v_mfma_f32_32x32x16_bf16 v[48:63], v[80:83], v[64:67], v[48:63]
	s_cmp_ge_i32 s45, s34
	v_mfma_f32_32x32x16_bf16 v[48:63], v[84:87], v[68:71], v[48:63]
	v_mfma_f32_32x32x16_bf16 v[48:63], v[88:91], v[72:75], v[48:63]
	v_mfma_f32_32x32x16_bf16 v[48:63], v[92:95], v[76:79], v[48:63]
	s_cbranch_scc1 .LBB0_545
	v_add_u32_e32 v106, s30, v150
	v_subrev_u32_e32 v96, 64, v106
	v_subrev_u32_e32 v98, 56, v106
	v_subrev_u32_e32 v104, 48, v106
	v_subrev_u32_e32 v106, 40, v106
	v_ashrrev_i32_e32 v97, 31, v96
	v_ashrrev_i32_e32 v99, 31, v98
	v_ashrrev_i32_e32 v105, 31, v104
	v_ashrrev_i32_e32 v107, 31, v106
	v_lshlrev_b64 v[96:97], 8, v[96:97]
	v_lshlrev_b64 v[98:99], 8, v[98:99]
	v_lshlrev_b64 v[104:105], 8, v[104:105]
	v_lshlrev_b64 v[106:107], 8, v[106:107]
	v_lshl_add_u64 v[208:209], v[176:177], 0, v[96:97]
	v_lshl_add_u64 v[212:213], v[176:177], 0, v[98:99]
	v_lshl_add_u64 v[216:217], v[176:177], 0, v[104:105]
	v_lshl_add_u64 v[220:221], v[176:177], 0, v[106:107]
	global_load_dwordx4 v[208:211], v[208:209], off
	s_nop 0
	global_load_dwordx4 v[212:215], v[212:213], off
	s_nop 0
	global_load_dwordx4 v[216:219], v[216:217], off
	s_nop 0
	global_load_dwordx4 v[220:223], v[220:221], off
	v_lshl_add_u64 v[96:97], v[126:127], 0, v[96:97]
	v_lshl_add_u64 v[100:101], v[126:127], 0, v[98:99]
	v_lshl_add_u64 v[104:105], v[126:127], 0, v[104:105]
	v_lshl_add_u64 v[108:109], v[126:127], 0, v[106:107]
	global_load_dwordx4 v[96:99], v[96:97], off
	s_nop 0
	global_load_dwordx4 v[100:103], v[100:101], off
	s_nop 0
	global_load_dwordx4 v[104:107], v[104:105], off
	s_nop 0
	global_load_dwordx4 v[108:111], v[108:109], off

; #define LAS __attribute__((address_space(3)))
; #define SA_LOAD(tbase) do { const bf16* kp_ = Kp + (size_t)((tbase) + r32) * kvpitch + 8 * hi; \
;         _Pragma("unroll") for (int ks = 0; ks < 4; ++ks) kf[ks] = *(const bf16x8*)(kp_ + 16 * ks); \
;         _Pragma("unroll") for (int e = 0; e < 4; ++e) { const int c = lane + 64 * e; vr[e] = *(const v4u*)(Vp + (size_t)((tbase) + (c >> 3)) * kvpitch + (c & 7) * 8); } } while (0)
; #define SA_VWRITE(buf) do { _Pragma("unroll") for (int e = 0; e < 4; ++e) { const int c = lane + 64 * e; *(LAS v4u*)(wl + (buf) * 4608 + (c >> 3) * 144 + (c & 7) * 16) = vr[e]; } } while (0)
; #define SA_QK(X) do { _Pragma("unroll") for (int ks = 0; ks < 4; ++ks) X = __builtin_amdgcn_mfma_f32_32x32x16_bf16(kf[ks], qf[ks], X, 0, 0, 0); } while (0)
; template <int MODE> ...
;     ...
;     SA_LOAD(tb0);
;     float bmx = -1e30f;
;     for (int e = lane; e < ntab; e += 64) { const float tv_ = gtab[e] * tabscale; tab[e] = tv_; bmx = fmaxf(bmx, tv_); }
; #pragma unroll
;     for (int o_ = 1; o_ < 64; o_ <<= 1) bmx = fmaxf(bmx, __shfl_xor(bmx, o_));
;     float ref;
;     { float qs = 0.f;
; #pragma unroll
;       for (int ks = 0; ks < 4; ++ks) { const v4u qw = __builtin_bit_cast(v4u, qf[ks]);
; #pragma unroll
;           for (int e = 0; e < 4; ++e) { const float lo_ = __uint_as_float(qw[e] << 16), hi_ = __uint_as_float(qw[e] & 0xffff0000u); qs += lo_ * lo_ + hi_ * hi_; } }
;       auto rr = __builtin_amdgcn_permlane32_swap(__float_as_uint(qs), __float_as_uint(qs), false, false); qs = __uint_as_float(rr[0]) + __uint_as_float(rr[1]);
;       const float k2 = __uint_as_float(kmax2[0]) + __uint_as_float(kmax2[1]);
;       ref = fminf(__builtin_sqrtf(qs * k2) * 1.03f + bmx, 110.0f); }
;     f32x16 o0 = {}, o1 = {};
;     float lsum = 0.f;
;     const int i16 = lane & 15, g16 = (lane >> 4) & 1;
;     LAS unsigned char* vaddr = wl + (4 * hi + (i16 >> 2)) * 144 + g16 * 32 + 8 * (i16 & 3);
;     f32x16 xa_, xb_;
;     SA_VWRITE(0); SA_CINIT(0, xa_); SA_QK(xa_);
;     if (nt > 1) SA_LOAD(tb0 + tstep);
.LBB0_547:
	v_add_f32_e32 v171, 0, v0
	v_add_f32_e32 v171, v1, v171
	v_add_f32_e32 v171, v2, v171
	v_add_f32_e32 v171, v3, v171
	v_add_f32_e32 v171, v4, v171
	v_add_f32_e32 v171, v5, v171
	v_add_f32_e32 v171, v6, v171
	v_add_f32_e32 v171, v7, v171
	v_add_f32_e32 v171, v8, v171
	v_add_f32_e32 v171, v9, v171
	v_add_f32_e32 v171, v10, v171
	v_add_f32_e32 v171, v11, v171
	v_add_f32_e32 v171, v12, v171
	v_add_f32_e32 v171, v13, v171
	v_add_f32_e32 v171, v14, v171
	v_add_f32_e32 v171, v15, v171
	s_andn2_b64 vcc, exec, s[0:1]
	v_add_f32_e32 v169, v169, v171
	s_cbranch_vccnz .LBB0_588
	s_add_i32 s4, s45, 2
	s_cmp_ge_i32 s4, s31
	s_cbranch_scc1 .LBB0_587
	s_add_i32 s0, s44, s30
	s_add_i32 s0, s0, 32
	s_cmpk_lt_u32 s0, 0xc1
	s_mov_b64 s[0:1], -1
	s_waitcnt vmcnt(4)
	ds_write_b128 v224, v[208:211]
	ds_write_b128 v224, v[212:215] offset:1152
	ds_write_b128 v224, v[216:219] offset:2304
	ds_write_b128 v224, v[220:223] offset:3456
	ds_read_b128 v[80:83], v225
	ds_read_b128 v[84:87], v225 offset:32
	ds_read_b128 v[88:91], v225 offset:64
	ds_read_b128 v[92:95], v225 offset:96
	s_waitcnt vmcnt(3)
	ds_write_b128 v166, v[96:99]
	s_waitcnt vmcnt(2)
	ds_write_b128 v166, v[100:103] offset:1152
	s_waitcnt vmcnt(1)
	ds_write_b128 v166, v[104:107] offset:2304
	s_waitcnt vmcnt(0)
	ds_write_b128 v166, v[108:111] offset:3456
	s_cbranch_scc1 .LBB0_583
	v_add_u32_e32 v171, s30, v170
	v_add_u32_e32 v0, 64, v171
	v_cmp_gt_u32_e32 vcc, s33, v0
	v_mov_b32_e32 v1, 0xf149f2ca
	v_mov_b32_e32 v0, 0xf149f2ca
	s_and_saveexec_b64 s[0:1], vcc
	ds_read_b32 v0, v128 offset:128
	s_or_b64 exec, exec, s[0:1]
	v_add_u32_e32 v2, 0x41, v171
	v_cmp_gt_u32_e32 vcc, s33, v2
	s_and_saveexec_b64 s[0:1], vcc
	ds_read_b32 v1, v128 offset:132
	s_or_b64 exec, exec, s[0:1]
	v_add_u32_e32 v2, 0x42, v171
	v_cmp_gt_u32_e32 vcc, s33, v2
	v_mov_b32_e32 v3, 0xf149f2ca
	v_mov_b32_e32 v2, 0xf149f2ca
	s_and_saveexec_b64 s[0:1], vcc
	ds_read_b32 v2, v128 offset:136
	s_or_b64 exec, exec, s[0:1]
	v_add_u32_e32 v4, 0x43, v171
	v_cmp_gt_u32_e32 vcc, s33, v4
	s_and_saveexec_b64 s[0:1], vcc
	ds_read_b32 v3, v128 offset:140
	s_or_b64 exec, exec, s[0:1]
	v_add_u32_e32 v4, 0x48, v171
	v_cmp_gt_u32_e32 vcc, s33, v4
	v_mov_b32_e32 v5, 0xf149f2ca
	v_mov_b32_e32 v4, 0xf149f2ca
	s_and_saveexec_b64 s[0:1], vcc
	ds_read_b32 v4, v128 offset:160
	s_or_b64 exec, exec, s[0:1]
	v_add_u32_e32 v6, 0x49, v171
	v_cmp_gt_u32_e32 vcc, s33, v6
	s_and_saveexec_b64 s[0:1], vcc
	ds_read_b32 v5, v128 offset:164
	s_or_b64 exec, exec, s[0:1]
	v_add_u32_e32 v6, 0x4a, v171
	v_cmp_gt_u32_e32 vcc, s33, v6
	v_mov_b32_e32 v7, 0xf149f2ca
	v_mov_b32_e32 v6, 0xf149f2ca
	s_and_saveexec_b64 s[0:1], vcc
	ds_read_b32 v6, v128 offset:168
	s_or_b64 exec, exec, s[0:1]
	v_add_u32_e32 v8, 0x4b, v171
	v_cmp_gt_u32_e32 vcc, s33, v8
	s_and_saveexec_b64 s[0:1], vcc
	ds_read_b32 v7, v128 offset:172
	s_or_b64 exec, exec, s[0:1]
	v_add_u32_e32 v8, 0x50, v171
	v_cmp_gt_u32_e32 vcc, s33, v8
	v_mov_b32_e32 v9, 0xf149f2ca
	v_mov_b32_e32 v8, 0xf149f2ca
	s_and_saveexec_b64 s[0:1], vcc
	ds_read_b32 v8, v128 offset:192
	s_or_b64 exec, exec, s[0:1]
	v_add_u32_e32 v10, 0x51, v171
	v_cmp_gt_u32_e32 vcc, s33, v10
	s_and_saveexec_b64 s[0:1], vcc
	ds_read_b32 v9, v128 offset:196
	s_or_b64 exec, exec, s[0:1]
	v_add_u32_e32 v10, 0x52, v171
	v_cmp_gt_u32_e32 vcc, s33, v10
	v_mov_b32_e32 v11, 0xf149f2ca
	v_mov_b32_e32 v10, 0xf149f2ca
	s_and_saveexec_b64 s[0:1], vcc
	ds_read_b32 v10, v128 offset:200
	s_or_b64 exec, exec, s[0:1]
	v_add_u32_e32 v12, 0x53, v171
	v_cmp_gt_u32_e32 vcc, s33, v12
	s_and_saveexec_b64 s[0:1], vcc
	ds_read_b32 v11, v128 offset:204
	s_or_b64 exec, exec, s[0:1]
	v_add_u32_e32 v12, 0x58, v171
	v_cmp_gt_u32_e32 vcc, s33, v12
	v_mov_b32_e32 v13, 0xf149f2ca
	v_mov_b32_e32 v12, 0xf149f2ca
	s_and_saveexec_b64 s[0:1], vcc
	ds_read_b32 v12, v128 offset:224
	s_or_b64 exec, exec, s[0:1]
	v_add_u32_e32 v14, 0x59, v171
	v_cmp_gt_u32_e32 vcc, s33, v14
	s_and_saveexec_b64 s[0:1], vcc
	ds_read_b32 v13, v128 offset:228
	s_or_b64 exec, exec, s[0:1]
	v_add_u32_e32 v14, 0x5a, v171
	v_cmp_gt_u32_e32 vcc, s33, v14
	v_mov_b32_e32 v15, 0xf149f2ca
	v_mov_b32_e32 v14, 0xf149f2ca
	s_and_saveexec_b64 s[0:1], vcc
	ds_read_b32 v14, v128 offset:232
	s_or_b64 exec, exec, s[0:1]
	v_add_u32_e32 v171, 0x5b, v171
	v_cmp_gt_u32_e32 vcc, s33, v171
	s_and_saveexec_b64 s[0:1], vcc
	ds_read_b32 v15, v128 offset:236
	s_or_b64 exec, exec, s[0:1]
	s_mov_b64 s[0:1], 0

.LBB0_585:
	s_waitcnt lgkmcnt(0)
	v_mfma_f32_32x32x16_bf16 v[0:15], v[80:83], v[64:67], v[0:15]
	s_cmp_ge_i32 s45, s37
	v_mfma_f32_32x32x16_bf16 v[0:15], v[84:87], v[68:71], v[0:15]
	v_mfma_f32_32x32x16_bf16 v[0:15], v[88:91], v[72:75], v[0:15]
	v_mfma_f32_32x32x16_bf16 v[0:15], v[92:95], v[76:79], v[0:15]
	s_cbranch_scc1 .LBB0_587
	v_add_u32_e32 v106, s30, v150
	v_subrev_u32_e32 v96, 32, v106
	v_subrev_u32_e32 v98, 24, v106
	v_add_u32_e32 v104, -16, v106
	v_add_u32_e32 v106, -8, v106
	v_ashrrev_i32_e32 v97, 31, v96
	v_ashrrev_i32_e32 v99, 31, v98
	v_ashrrev_i32_e32 v105, 31, v104
	v_ashrrev_i32_e32 v107, 31, v106
	v_lshlrev_b64 v[96:97], 8, v[96:97]
	v_lshlrev_b64 v[98:99], 8, v[98:99]
	v_lshlrev_b64 v[104:105], 8, v[104:105]
	v_lshlrev_b64 v[106:107], 8, v[106:107]
	v_lshl_add_u64 v[208:209], v[176:177], 0, v[96:97]
	v_lshl_add_u64 v[212:213], v[176:177], 0, v[98:99]
	v_lshl_add_u64 v[216:217], v[176:177], 0, v[104:105]
	v_lshl_add_u64 v[220:221], v[176:177], 0, v[106:107]
	global_load_dwordx4 v[208:211], v[208:209], off
	s_nop 0
	global_load_dwordx4 v[212:215], v[212:213], off
	s_nop 0
	global_load_dwordx4 v[216:219], v[216:217], off
	s_nop 0
	global_load_dwordx4 v[220:223], v[220:221], off
	v_lshl_add_u64 v[96:97], v[126:127], 0, v[96:97]
	v_lshl_add_u64 v[100:101], v[126:127], 0, v[98:99]
	v_lshl_add_u64 v[104:105], v[126:127], 0, v[104:105]
	v_lshl_add_u64 v[108:109], v[126:127], 0, v[106:107]
	global_load_dwordx4 v[96:99], v[96:97], off
	s_nop 0
	global_load_dwordx4 v[100:103], v[100:101], off
	s_nop 0
	global_load_dwordx4 v[104:107], v[104:105], off
	s_nop 0
	global_load_dwordx4 v[108:111], v[108:109], off
